# DeltaNet chunkwise WY form on f32 matrix cores, with the barrier after the prefetch section restored at the chunk code entry
# baseline (speedup 1.0000x reference)
; __device__ __forceinline__ void dn_task(const Params& p, int l, int task, char* smem) {
;     ...
;     __syncthreads();
;     if (n + 1 < 72) DN_PREFETCH(n + 1);
;     {
;       const int did = tid >> 2, pp = did >> 2, wh = did & 3, part = tid & 3;
;       const float* xr = (wh == 0) ? (ks + (2 * pp + 1) * 68) : (wh == 1) ? (qs + (2 * pp) * 68) : (qs + (2 * pp + 1) * 68);
;       const float* yr = (wh == 3) ? (ks + (2 * pp + 1) * 68) : (ks + (2 * pp) * 68);
;       float sdot = 0.f;
; #pragma unroll
;       for (int i = 0; i < 16; ++i) sdot += xr[part * 16 + i] * yr[part * 16 + i];
;       sdot = quad_sum(sdot);
;       if (part == 0) dots[did] = sdot;
;     }
;     __syncthreads();
.LBB0_207:
	s_waitcnt lgkmcnt(0)
	s_barrier
	v_and_b32_e32 v221, 63, v172
	v_and_b32_e32 v222, 15, v221
	v_lshrrev_b32_e32 v223, 4, v221
	v_mul_u32_u24_e32 v224, 0x110, v222
	v_lshl_add_u32 v224, v223, 6, v224
	v_mul_u32_u24_e32 v225, 0x240, v223
	v_lshl_add_u32 v225, v222, 2, v225
	v_readfirstlane_b32 s60, v172
	s_nop 3
	s_lshr_b32 s60, s60, 6
	v_lshrrev_b32_e32 v244, 3, v172
	v_lshlrev_b32_e32 v244, 2, v244
	v_sub_u32_e32 v248, v167, v244
	s_and_b32 s61, s60, 1
	s_lshl_b32 s61, s61, 6
	v_mul_u32_u24_e32 v244, 0x840, v223
	v_lshl_add_u32 v244, v222, 2, v244
	s_add_i32 s61, s61, 0x11600
	v_add_u32_e32 v244, s61, v244
	ds_read_b32 v10, v244 offset:0
	ds_read_b32 v11, v244 offset:132
	ds_read_b32 v12, v244 offset:264
	ds_read_b32 v13, v244 offset:396
	ds_read_b32 v14, v244 offset:528
	ds_read_b32 v15, v244 offset:660
	ds_read_b32 v16, v244 offset:792
	ds_read_b32 v17, v244 offset:924
	ds_read_b32 v18, v244 offset:1056
	ds_read_b32 v19, v244 offset:1188
	ds_read_b32 v20, v244 offset:1320
	ds_read_b32 v21, v244 offset:1452
	ds_read_b32 v22, v244 offset:1584
	ds_read_b32 v23, v244 offset:1716
	ds_read_b32 v24, v244 offset:1848
	ds_read_b32 v25, v244 offset:1980
	s_lshr_b32 s61, s60, 1
	s_mul_i32 s70, s61, 0x1100
	v_add_u32_e32 v246, s70, v224
	ds_read_b128 v[66:69], v246 offset:8704
	ds_read_b128 v[70:73], v246 offset:8720
	ds_read_b128 v[74:77], v246 offset:8736
	ds_read_b128 v[78:81], v246 offset:8752
	s_cmp_eq_u32 s60, 3
	s_cbranch_scc1 .Ldc_w3
	s_cmp_ge_u32 s60, 1
	s_cselect_b32 s61, 0x1100, 0
	s_cmp_eq_u32 s60, 2
	s_cselect_b32 s70, 0x1100, 0
	v_add_u32_e32 v244, s61, v224
	v_add_u32_e32 v245, s70, v224
	ds_read_b128 v[26:29], v244 offset:8704
	ds_read_b128 v[30:33], v244 offset:8720
	ds_read_b128 v[34:37], v244 offset:8736
	ds_read_b128 v[38:41], v244 offset:8752
	ds_read_b128 v[42:45], v245 offset:8704
	ds_read_b128 v[46:49], v245 offset:8720
	ds_read_b128 v[50:53], v245 offset:8736
	ds_read_b128 v[54:57], v245 offset:8752
	s_waitcnt lgkmcnt(0)
	v_mfma_f32_16x16x4_f32 v[62:65], v66, v10, 0
	v_mfma_f32_16x16x4_f32 v[58:61], v26, v42, 0
	v_mfma_f32_16x16x4_f32 v[62:65], v67, v11, v[62:65]
	v_mfma_f32_16x16x4_f32 v[58:61], v27, v43, v[58:61]
	v_mfma_f32_16x16x4_f32 v[62:65], v68, v12, v[62:65]
	v_mfma_f32_16x16x4_f32 v[58:61], v28, v44, v[58:61]
	v_mfma_f32_16x16x4_f32 v[62:65], v69, v13, v[62:65]
	v_mfma_f32_16x16x4_f32 v[58:61], v29, v45, v[58:61]
	v_mfma_f32_16x16x4_f32 v[62:65], v70, v14, v[62:65]
	v_mfma_f32_16x16x4_f32 v[58:61], v30, v46, v[58:61]
	v_mfma_f32_16x16x4_f32 v[62:65], v71, v15, v[62:65]
	v_mfma_f32_16x16x4_f32 v[58:61], v31, v47, v[58:61]
	v_mfma_f32_16x16x4_f32 v[62:65], v72, v16, v[62:65]
	v_mfma_f32_16x16x4_f32 v[58:61], v32, v48, v[58:61]
	v_mfma_f32_16x16x4_f32 v[62:65], v73, v17, v[62:65]
	v_mfma_f32_16x16x4_f32 v[58:61], v33, v49, v[58:61]
	v_mfma_f32_16x16x4_f32 v[62:65], v74, v18, v[62:65]
	v_mfma_f32_16x16x4_f32 v[58:61], v34, v50, v[58:61]
	v_mfma_f32_16x16x4_f32 v[62:65], v75, v19, v[62:65]
	v_mfma_f32_16x16x4_f32 v[58:61], v35, v51, v[58:61]
	v_mfma_f32_16x16x4_f32 v[62:65], v76, v20, v[62:65]
	v_mfma_f32_16x16x4_f32 v[58:61], v36, v52, v[58:61]
	v_mfma_f32_16x16x4_f32 v[62:65], v77, v21, v[62:65]
	v_mfma_f32_16x16x4_f32 v[58:61], v37, v53, v[58:61]
	v_mfma_f32_16x16x4_f32 v[62:65], v78, v22, v[62:65]
	v_mfma_f32_16x16x4_f32 v[58:61], v38, v54, v[58:61]
	v_mfma_f32_16x16x4_f32 v[62:65], v79, v23, v[62:65]
	v_mfma_f32_16x16x4_f32 v[58:61], v39, v55, v[58:61]
	v_mfma_f32_16x16x4_f32 v[62:65], v80, v24, v[62:65]
	v_mfma_f32_16x16x4_f32 v[58:61], v40, v56, v[58:61]
	v_mfma_f32_16x16x4_f32 v[62:65], v81, v25, v[62:65]
	v_mfma_f32_16x16x4_f32 v[58:61], v41, v57, v[58:61]
	s_branch .Ldc_b1
